# wave stagger: s_sleep 6 after the followers' top barrier and s_sleep 2 after the leaders' head barrier (followers' QK phase and leaders' load/QK phase had slack; de-synchronises the two waves of a SIM
# speedup vs baseline: 1.0254x; 1.0118x over previous
.LBB0_226:
	s_lshl_b32 s86, s33, 15
	v_or_b32_e32 v102, s86, v200
	s_waitcnt lgkmcnt(0)
	s_barrier
	s_sleep 6
	v_add_u32_e32 v129, v102, v202
	ds_read_b128 v[98:101], v129
	v_add_u32_e32 v151, v102, v203
	v_add_f32_e32 v232, s74, v162
	v_add_f32_e32 v233, s75, v162
	v_add_f32_e32 v234, s64, v162
	v_add_f32_e32 v235, s65, v162
	v_add_f32_e32 v236, s58, v162
	v_add_f32_e32 v237, s59, v162
	v_add_f32_e32 v238, s56, v162
	v_add_f32_e32 v239, s57, v162
	s_waitcnt vmcnt(3) lgkmcnt(0)
	v_mfma_f32_32x32x16_bf16 v[216:231], v[98:101], v[82:85], v[216:231]
	ds_read_b128 v[98:101], v151
	v_add_u32_e32 v157, v102, v204
	v_add_u32_e32 v161, v102, v205
	s_add_i32 s6, s33, 1
	v_add_u32_e32 v128, 1, v128
	s_cmp_lg_u32 s33, 2
	v_cmp_ge_i32_e32 vcc, v128, v155
	v_add_f32_e32 v240, s54, v162
	v_add_f32_e32 v241, s55, v162
	v_add_f32_e32 v242, s48, v162
	v_add_f32_e32 v243, s49, v162
	s_waitcnt vmcnt(2) lgkmcnt(0)
	v_mfma_f32_32x32x16_bf16 v[216:231], v[98:101], v[86:89], v[216:231]
	ds_read_b128 v[98:101], v157
	s_cselect_b32 s33, s6, 0
	v_add_u32_e32 v127, 64, v127
	s_or_b64 s[84:85], vcc, s[84:85]
	v_add_f32_e32 v244, s34, v162
	v_add_f32_e32 v245, s35, v162
	v_add_f32_e32 v246, s30, v162
	v_add_f32_e32 v247, s31, v162
	v_fma_f32 v232, v106, |v232|, v146
	v_fma_f32 v233, v106, |v233|, v146
	s_waitcnt vmcnt(1) lgkmcnt(0)
	v_mfma_f32_32x32x16_bf16 v[216:231], v[98:101], v[90:93], v[216:231]
	ds_read_b128 v[98:101], v161
	v_fma_f32 v234, v106, |v234|, v146
	v_fma_f32 v235, v106, |v235|, v146
	v_fma_f32 v236, v106, |v236|, v146
	v_fma_f32 v237, v106, |v237|, v146
	v_fma_f32 v238, v106, |v238|, v146
	v_fma_f32 v239, v106, |v239|, v146
	s_waitcnt vmcnt(0) lgkmcnt(0)
	v_mfma_f32_32x32x16_bf16 v[216:231], v[98:101], v[94:97], v[216:231]
	ds_read_b128 v[162:165], v129 offset:8192
	v_fma_f32 v240, v106, |v240|, v146
	v_fma_f32 v241, v106, |v241|, v146
	v_fma_f32 v242, v106, |v242|, v146
	v_fma_f32 v243, v106, |v243|, v146
	v_fma_f32 v244, v106, |v244|, v146
	v_fma_f32 v245, v106, |v245|, v146
	v_fma_f32 v246, v106, |v246|, v146
	v_fma_f32 v247, v106, |v247|, v146
	s_nop 2
	v_exp_f32_e32 v66, v216
	v_exp_f32_e32 v166, v217
	v_exp_f32_e32 v168, v218
	v_exp_f32_e32 v170, v219
	v_add_f32_e32 v132, 0, v66
	s_waitcnt lgkmcnt(0)
	v_mfma_f32_32x32x16_bf16 v[232:247], v[162:165], v[82:85], v[232:247]
	ds_read_b128 v[162:165], v151 offset:8192
	v_exp_f32_e32 v188, v228
	v_exp_f32_e32 v212, v229
	v_exp_f32_e32 v214, v230
	v_exp_f32_e32 v250, v231
	v_cvt_pk_bf16_f32 v98, v66, v166
	s_waitcnt lgkmcnt(0)
	v_mfma_f32_32x32x16_bf16 v[232:247], v[162:165], v[86:89], v[232:247]
	ds_read_b128 v[162:165], v157 offset:8192
	v_exp_f32_e32 v172, v220
	v_exp_f32_e32 v174, v221
	v_exp_f32_e32 v176, v222
	v_exp_f32_e32 v178, v223
	s_waitcnt lgkmcnt(0)
	v_mfma_f32_32x32x16_bf16 v[232:247], v[162:165], v[90:93], v[232:247]
	ds_read_b128 v[162:165], v161 offset:8192
	v_exp_f32_e32 v180, v224
	v_exp_f32_e32 v182, v225
	v_exp_f32_e32 v184, v226
	v_exp_f32_e32 v186, v227
	s_waitcnt lgkmcnt(0)
	s_barrier
	s_waitcnt lgkmcnt(0)
	v_mfma_f32_32x32x16_bf16 v[232:247], v[162:165], v[94:97], v[232:247]
	v_cvt_pk_bf16_f32 v99, v168, v170
	v_cvt_pk_bf16_f32 v100, v172, v174
	v_cvt_pk_bf16_f32 v101, v176, v178
	v_cvt_pk_bf16_f32 v102, v180, v182
	v_cvt_pk_bf16_f32 v103, v184, v186
	v_cvt_pk_bf16_f32 v104, v188, v212
	v_cvt_pk_bf16_f32 v105, v214, v250
	v_or_b32_e32 v80, s86, v193
	v_add_u32_e32 v81, v80, v195
	ds_read_b128 v[74:77], v81 offset:16384
	v_add_u32_e32 v129, v80, v196
	s_nop 0
	v_exp_f32_e32 v251, v246
	v_exp_f32_e32 v161, v247
	v_exp_f32_e32 v183, v240
	v_exp_f32_e32 v185, v241
	v_exp_f32_e32 v187, v242
	v_exp_f32_e32 v189, v243
	s_waitcnt lgkmcnt(0)
	v_mfma_f32_32x32x16_bf16 v[50:65], v[74:77], v[98:101], v[50:65]
	ds_read_b128 v[74:77], v129 offset:16384
	v_exp_f32_e32 v167, v232
	v_exp_f32_e32 v169, v233
	v_exp_f32_e32 v171, v234
	v_exp_f32_e32 v173, v235
	v_pk_add_f32 v[66:67], v[166:167], v[132:133]
	v_exp_f32_e32 v175, v236
	s_waitcnt lgkmcnt(0)
	v_mfma_f32_32x32x16_bf16 v[50:65], v[74:77], v[102:105], v[50:65]
	ds_read_b128 v[74:77], v81 offset:20480
	v_add_f32_e64 v66, v168, v66
	v_add_f32_e64 v67, v169, v67
	v_exp_f32_e32 v177, v237
	v_pk_add_f32 v[66:67], v[170:171], v[66:67]
	v_exp_f32_e32 v179, v238
	v_pk_add_f32 v[66:67], v[172:173], v[66:67]
	v_exp_f32_e32 v181, v239
	s_waitcnt lgkmcnt(0)
	v_mfma_f32_32x32x16_bf16 v[34:49], v[74:77], v[98:101], v[34:49]
	ds_read_b128 v[74:77], v129 offset:20480
	v_add_f32_e64 v66, v174, v66
	v_add_f32_e64 v67, v175, v67
	v_exp_f32_e32 v213, v244
	v_pk_add_f32 v[66:67], v[176:177], v[66:67]
	v_exp_f32_e32 v215, v245
	v_pk_add_f32 v[66:67], v[178:179], v[66:67]
	v_cvt_pk_bf16_f32 v68, v175, v177
	s_waitcnt lgkmcnt(0)
	v_mfma_f32_32x32x16_bf16 v[34:49], v[74:77], v[102:105], v[34:49]
	ds_read_b128 v[74:77], v81 offset:24576
	v_add_f32_e64 v66, v180, v66
	v_add_f32_e64 v67, v181, v67
	v_cvt_pk_bf16_f32 v69, v179, v181
	v_add_f32_e64 v66, v182, v66
	v_add_f32_e64 v67, v183, v67
	v_cvt_pk_bf16_f32 v70, v183, v185
	v_pk_add_f32 v[66:67], v[184:185], v[66:67]
	v_cvt_pk_bf16_f32 v71, v187, v189
	s_waitcnt lgkmcnt(0)
	v_mfma_f32_32x32x16_bf16 v[18:33], v[74:77], v[98:101], v[18:33]
	ds_read_b128 v[74:77], v129 offset:24576
	v_add_f32_e64 v66, v186, v66
	v_add_f32_e64 v67, v187, v67
	v_cvt_pk_bf16_f32 v72, v213, v215
	v_add_f32_e64 v66, v188, v66
	v_add_f32_e64 v67, v189, v67
	v_cvt_pk_bf16_f32 v73, v251, v161
	v_pk_add_f32 v[66:67], v[212:213], v[66:67]
	s_waitcnt lgkmcnt(0)
	v_mfma_f32_32x32x16_bf16 v[18:33], v[74:77], v[102:105], v[18:33]
	ds_read_b128 v[74:77], v81 offset:28672
	v_add_u32_e32 v81, v80, v197
	v_add_f32_e64 v66, v214, v66
	v_add_f32_e64 v67, v215, v67
	v_add_u32_e32 v80, v80, v198
	v_pk_add_f32 v[66:67], v[250:251], v[66:67]
	s_nop 0
	v_pk_add_f32 v[78:79], v[160:161], v[66:67]
	s_waitcnt lgkmcnt(0)
	v_mfma_f32_32x32x16_bf16 v[2:17], v[74:77], v[98:101], v[2:17]
	ds_read_b128 v[74:77], v129 offset:28672
	v_cvt_pk_bf16_f32 v66, v167, v169
	v_cvt_pk_bf16_f32 v67, v171, v173
	v_add_f32_e32 v160, v78, v79
	s_waitcnt lgkmcnt(0)
	v_mfma_f32_32x32x16_bf16 v[2:17], v[74:77], v[102:105], v[2:17]
	ds_read_b128 v[74:77], v81 offset:16384
	v_cvt_f32_i32_e32 v162, v127
	v_add_f32_e32 v217, 1.0, v162
	v_add_f32_e32 v218, s12, v162
	v_add_f32_e32 v219, s13, v162
	s_waitcnt lgkmcnt(0)
	v_mfma_f32_32x32x16_bf16 v[50:65], v[74:77], v[66:69], v[50:65]
	ds_read_b128 v[74:77], v80 offset:16384
	v_add_f32_e32 v220, s16, v162
	v_add_f32_e32 v221, s17, v162
	v_add_f32_e32 v222, s18, v162
	v_add_f32_e32 v223, s19, v162
	s_waitcnt lgkmcnt(0)
	v_mfma_f32_32x32x16_bf16 v[50:65], v[74:77], v[70:73], v[50:65]
	ds_read_b128 v[74:77], v81 offset:20480
	v_add_f32_e32 v224, s20, v162
	v_add_f32_e32 v225, s21, v162
	v_add_f32_e32 v226, s22, v162
	v_add_f32_e32 v227, s23, v162
	s_waitcnt lgkmcnt(0)
	v_mfma_f32_32x32x16_bf16 v[34:49], v[74:77], v[66:69], v[34:49]
	ds_read_b128 v[74:77], v80 offset:20480
	v_add_f32_e32 v228, s26, v162
	v_add_f32_e32 v229, s27, v162
	v_add_f32_e32 v230, s28, v162
	v_add_f32_e32 v231, s29, v162
	s_waitcnt lgkmcnt(0)
	v_mfma_f32_32x32x16_bf16 v[34:49], v[74:77], v[70:73], v[34:49]
	ds_read_b128 v[74:77], v81 offset:24576
	v_fma_f32 v216, v106, |v162|, v146
	v_fma_f32 v217, v106, |v217|, v146
	v_fma_f32 v218, v106, |v218|, v146
	v_fma_f32 v219, v106, |v219|, v146
	s_waitcnt lgkmcnt(0)
	v_mfma_f32_32x32x16_bf16 v[18:33], v[74:77], v[66:69], v[18:33]
	ds_read_b128 v[74:77], v80 offset:24576
	v_fma_f32 v220, v106, |v220|, v146
	v_fma_f32 v221, v106, |v221|, v146
	v_fma_f32 v222, v106, |v222|, v146
	v_fma_f32 v223, v106, |v223|, v146
	s_waitcnt lgkmcnt(0)
	v_mfma_f32_32x32x16_bf16 v[18:33], v[74:77], v[70:73], v[18:33]
	ds_read_b128 v[74:77], v81 offset:28672
	v_fma_f32 v224, v106, |v224|, v146
	v_fma_f32 v225, v106, |v225|, v146
	v_fma_f32 v226, v106, |v226|, v146
	v_fma_f32 v227, v106, |v227|, v146
	s_waitcnt lgkmcnt(0)
	v_mfma_f32_32x32x16_bf16 v[2:17], v[74:77], v[66:69], v[2:17]
	ds_read_b128 v[66:69], v80 offset:28672
	v_fma_f32 v228, v106, |v228|, v146
	v_fma_f32 v229, v106, |v229|, v146
	v_fma_f32 v230, v106, |v230|, v146
	v_fma_f32 v231, v106, |v231|, v146
	s_waitcnt lgkmcnt(0)
	v_mfma_f32_32x32x16_bf16 v[2:17], v[66:69], v[70:73], v[2:17]
	s_andn2_b64 exec, exec, s[84:85]
	s_cbranch_execnz .LBB0_226
	s_or_b64 exec, exec, s[84:85]

.LBB0_233:
	s_waitcnt vmcnt(0)
	s_waitcnt lgkmcnt(0)
	s_barrier
	s_sleep 2
	s_add_i32 s6, s90, 1
	s_cmp_lg_u32 s90, 2
	s_cselect_b32 s33, s6, 0
	v_cmp_ge_i32_e32 vcc, v141, v155
	v_add_u32_e32 v126, 64, v66
	s_mov_b64 s[86:87], 0
	s_cbranch_vccnz .LBB0_232
	v_readfirstlane_b32 s98, v126
	v_readfirstlane_b32 s99, v191
	s_lshl_b32 s6, s33, 15
	s_mov_b32 s101, 0
	s_mov_b32 s7, 0
	s_add_i32 s99, s99, s6
	s_lshl_b32 s100, s98, 11
	s_lshl_b32 s6, s98, 1
	v_lshl_add_u64 v[70:71], v[106:107], 0, s[100:101]
	s_mov_b32 m0, s99
	s_add_u32 s100, s100, 0x8000
	global_load_lds_dwordx4 v[70:71], off
	v_lshl_add_u64 v[68:69], v[108:109], 0, s[6:7]
	s_add_i32 m0, s99, 0x4000
	s_add_u32 s6, s6, 0x40000
	global_load_lds_dwordx4 v[68:69], off
	v_lshl_add_u64 v[70:71], v[106:107], 0, s[100:101]
	s_add_i32 m0, s99, 0x1000
	s_add_u32 s100, s100, 0x8000
	global_load_lds_dwordx4 v[70:71], off
	v_lshl_add_u64 v[68:69], v[108:109], 0, s[6:7]
	s_add_i32 m0, s99, 0x5000
	s_add_u32 s6, s6, 0x40000
	global_load_lds_dwordx4 v[68:69], off
	v_lshl_add_u64 v[70:71], v[106:107], 0, s[100:101]
	s_add_i32 m0, s99, 0x2000
	s_add_u32 s100, s100, 0x8000
	global_load_lds_dwordx4 v[70:71], off
	v_lshl_add_u64 v[68:69], v[108:109], 0, s[6:7]
	s_add_i32 m0, s99, 0x6000
	s_add_u32 s6, s6, 0x40000
	global_load_lds_dwordx4 v[68:69], off
	v_lshl_add_u64 v[70:71], v[106:107], 0, s[100:101]
	s_add_i32 m0, s99, 0x3000
	s_add_u32 s100, s100, 0x8000
	global_load_lds_dwordx4 v[70:71], off
	v_lshl_add_u64 v[68:69], v[108:109], 0, s[6:7]
	s_add_i32 m0, s99, 0x7000
	s_add_u32 s6, s6, 0x40000
	global_load_lds_dwordx4 v[68:69], off
	s_branch .LBB0_232
